# c37: window-attention interior tiles fetch each bias pair with one ds_read2_b32 and write the exponentials straight into their final registers
# baseline (speedup 1.0000x reference)
; __device__ __forceinline__ int crow(int r, int hi) { return (r & 3) + 8 * (r >> 2) + 4 * hi; }
; __device__ void attn_b_item(const Params& p, int item, int l, unsigned char* smem) {
;     ...
;         for (int i = 0; i < 16; ++i) {
;             const int kv0 = kbase + crow(i, hi), kv1 = kv0 + 32;
;             const int rel0 = kv0 - qpos, rel1 = kv1 - qpos;
;             const bool ok0 = rel0 >= -64 && rel0 <= 64 && kv0 >= seq_lo && kv0 < seq_hi;
;             const bool ok1 = rel1 >= -64 && rel1 <= 64 && kv1 >= seq_lo && kv1 < seq_hi;
;             const float e0 = __builtin_amdgcn_exp2f(p0[i] + lut[ok0 ? rel0 + 64 : 64]);
;             const float e1 = __builtin_amdgcn_exp2f(p1[i] + lut[ok1 ? rel1 + 64 : 64]);
;             p0[i] = ok0 ? e0 : 0.f; p1[i] = ok1 ? e1 : 0.f;
;         }
.Latb_fast:
	v_lshl_add_u32 v182, v143, 2, s9
	ds_read2_b32 v[148:149], v182 offset0:0 offset1:32
	ds_read2_b32 v[150:151], v182 offset0:1 offset1:33
	ds_read2_b32 v[152:153], v182 offset0:2 offset1:34
	ds_read2_b32 v[154:155], v182 offset0:3 offset1:35
	s_waitcnt lgkmcnt(3)
	v_add_f32_e32 v181, v64, v148
	v_add_f32_e32 v64, v48, v149
	v_exp_f32_e32 v48, v181
	v_exp_f32_e32 v64, v64
	s_waitcnt lgkmcnt(2)
	v_add_f32_e32 v181, v65, v150
	v_add_f32_e32 v65, v49, v151
	v_exp_f32_e32 v49, v181
	v_exp_f32_e32 v65, v65
	s_waitcnt lgkmcnt(1)
	v_add_f32_e32 v181, v66, v152
	v_add_f32_e32 v66, v50, v153
	v_exp_f32_e32 v50, v181
	v_exp_f32_e32 v66, v66
	s_waitcnt lgkmcnt(0)
	v_add_f32_e32 v181, v67, v154
	v_add_f32_e32 v67, v51, v155
	v_exp_f32_e32 v51, v181
	v_exp_f32_e32 v67, v67
	ds_read2_b32 v[156:157], v182 offset0:8 offset1:40
	ds_read2_b32 v[158:159], v182 offset0:9 offset1:41
	ds_read2_b32 v[160:161], v182 offset0:10 offset1:42
	ds_read2_b32 v[162:163], v182 offset0:11 offset1:43
	s_waitcnt lgkmcnt(3)
	v_add_f32_e32 v181, v68, v156
	v_add_f32_e32 v68, v52, v157
	v_exp_f32_e32 v52, v181
	v_exp_f32_e32 v68, v68
	s_waitcnt lgkmcnt(2)
	v_add_f32_e32 v181, v69, v158
	v_add_f32_e32 v69, v53, v159
	v_exp_f32_e32 v53, v181
	v_exp_f32_e32 v69, v69
	s_waitcnt lgkmcnt(1)
	v_add_f32_e32 v181, v70, v160
	v_add_f32_e32 v70, v54, v161
	v_exp_f32_e32 v54, v181
	v_exp_f32_e32 v70, v70
	s_waitcnt lgkmcnt(0)
	v_add_f32_e32 v181, v71, v162
	v_add_f32_e32 v71, v55, v163
	v_exp_f32_e32 v55, v181
	v_exp_f32_e32 v71, v71
	ds_read2_b32 v[164:165], v182 offset0:16 offset1:48
	ds_read2_b32 v[166:167], v182 offset0:17 offset1:49
	ds_read2_b32 v[168:169], v182 offset0:18 offset1:50
	ds_read2_b32 v[170:171], v182 offset0:19 offset1:51
	s_waitcnt lgkmcnt(3)
	v_add_f32_e32 v181, v72, v164
	v_add_f32_e32 v72, v56, v165
	v_exp_f32_e32 v56, v181
	v_exp_f32_e32 v72, v72
	s_waitcnt lgkmcnt(2)
	v_add_f32_e32 v181, v73, v166
	v_add_f32_e32 v73, v57, v167
	v_exp_f32_e32 v57, v181
	v_exp_f32_e32 v73, v73
	s_waitcnt lgkmcnt(1)
	v_add_f32_e32 v181, v74, v168
	v_add_f32_e32 v74, v58, v169
	v_exp_f32_e32 v58, v181
	v_exp_f32_e32 v74, v74
	s_waitcnt lgkmcnt(0)
	v_add_f32_e32 v181, v75, v170
	v_add_f32_e32 v75, v59, v171
	v_exp_f32_e32 v59, v181
	v_exp_f32_e32 v75, v75
	ds_read2_b32 v[172:173], v182 offset0:24 offset1:56
	ds_read2_b32 v[174:175], v182 offset0:25 offset1:57
	ds_read2_b32 v[176:177], v182 offset0:26 offset1:58
	ds_read2_b32 v[178:179], v182 offset0:27 offset1:59
	s_waitcnt lgkmcnt(3)
	v_add_f32_e32 v181, v76, v172
	v_add_f32_e32 v76, v60, v173
	v_exp_f32_e32 v60, v181
	v_exp_f32_e32 v76, v76
	s_waitcnt lgkmcnt(2)
	v_add_f32_e32 v181, v77, v174
	v_add_f32_e32 v77, v61, v175
	v_exp_f32_e32 v61, v181
	v_exp_f32_e32 v77, v77
	s_waitcnt lgkmcnt(1)
	v_add_f32_e32 v181, v78, v176
	v_add_f32_e32 v78, v62, v177
	v_exp_f32_e32 v62, v181
	v_exp_f32_e32 v78, v78
	s_waitcnt lgkmcnt(0)
	v_add_f32_e32 v181, v79, v178
	v_add_f32_e32 v79, v63, v179
	v_exp_f32_e32 v63, v181
	v_exp_f32_e32 v79, v79
